# phase0: weight and workspace base pointers loaded once before the item loop (no scalar kernarg loads + waits per item)
# baseline (speedup 1.0000x reference)
.LBB0_22:
	s_or_b64 exec, exec, s[4:5]
	s_mov_b32 s30, s94
	s_waitcnt lgkmcnt(0)
	s_barrier
	s_cmpk_gt_i32 s30, 0x1850
	s_cbranch_scc1 .LBB0_80
	v_and_b32_e32 v12, 63, v8
	v_ashrrev_i32_e32 v14, 6, v8
	v_lshl_add_u32 v0, v12, 2, 0
	s_movk_i32 s31, 0x300
	v_mad_u64_u32 v[20:21], s[4:5], v14, s31, v[0:1]
	v_lshlrev_b32_e32 v10, 3, v8
	v_lshlrev_b32_e32 v16, 7, v14
	s_movk_i32 s4, 0xc0
	v_lshlrev_b32_e32 v1, 8, v14
	s_mov_b32 s16, 0x6dc9c883
	s_mov_b32 s18, 0x54442d18
	v_ashrrev_i32_e32 v11, 31, v10
	v_ashrrev_i32_e32 v17, 31, v16
	v_mov_b32_e32 v19, 0
	s_mov_b32 s15, 0
	v_lshl_add_u32 v9, v14, 9, 0
	v_cmp_gt_i32_e64 s[4:5], s4, v8
	s_movk_i32 s34, 0x104
	s_movk_i32 s35, 0x1600
	s_movk_i32 s38, 0x5800
	s_movk_i32 s39, 0x880
	s_movk_i32 s40, 0xc00
	s_movk_i32 s41, 0x1f00
	s_mov_b32 s42, 0x2aaaaaab
	s_movk_i32 s43, 0xffe8
	s_mov_b32 s44, 0xc2fc0000
	s_mov_b32 s17, 0x3fc45f30
	s_mov_b32 s19, 0xc01921fb
	s_brev_b32 s45, 18
	s_mov_b32 s46, 0xfe5163ab
	s_mov_b32 s47, 0x3c439041
	s_mov_b32 s48, 0xdb629599
	s_mov_b32 s49, 0xf534ddc0
	s_mov_b32 s50, 0xfc2757d1
	s_mov_b32 s51, 0x4e441529
	s_mov_b32 s52, 0xa2f9836e
	s_mov_b32 s53, 0x3fc90fda
	s_mov_b32 s54, 0x3f22f983
	s_mov_b32 s55, 0xbfc90fda
	v_mov_b32_e32 v13, 0x3c0881c4
	v_mov_b32_e32 v15, 0xbab64f3b
	s_brev_b32 s56, 1
	s_movk_i32 s57, 0x1f8
	s_movk_i32 s58, 0x9ff
	s_movk_i32 s59, 0x6000
	s_mov_b32 s60, 0xc000
	s_mov_b32 s61, 0x12000
	s_mov_b32 s62, 0x18000
	s_mov_b32 s63, 0x1e000
	s_mov_b32 s64, 0x24000
	s_mov_b32 s65, 0x2a000
	v_add_u32_e32 v21, v0, v1
	v_mov_b32_e32 v24, 0x41000000
	v_mov_b32_e32 v25, 0x41800000
	v_mov_b32_e32 v26, 0x42800000
	v_not_b32_e32 v27, 63
	v_not_b32_e32 v28, 31
	v_mov_b32_e32 v29, 0x7fc00000
	v_mov_b32_e32 v30, 0x31a8000
	v_mov_b32_e32 v31, 0x31a4000
	s_load_dwordx2 s[76:77], s[0:1], 0xf0
	s_load_dwordx2 s[78:79], s[0:1], 0xb8
	s_load_dwordx2 s[80:81], s[0:1], 0xd0
	s_load_dwordx2 s[82:83], s[0:1], 0xa0
	s_load_dwordx2 s[84:85], s[0:1], 0x30
	s_waitcnt lgkmcnt(0)
	s_branch .LBB0_26

.LBB0_26:
	s_cmpk_gt_i32 s30, 0xbf
	s_mov_b64 s[6:7], -1
	s_cbranch_scc0 .LBB0_73
	s_cmpk_lg_i32 s30, 0xc0
	s_cbranch_scc0 .LBB0_61
	s_add_i32 s8, s30, 0xffffff3f
	s_cmpk_gt_u32 s8, 0xbc7
	s_mov_b64 s[6:7], s[76:77]
	s_cselect_b64 s[12:13], -1, 0
	s_add_i32 s9, s30, 0xfffff377
	s_cmpk_lt_u32 s8, 0xbc8
	s_cselect_b32 s22, s8, s9
	s_and_b64 s[8:9], s[12:13], exec
	s_cselect_b32 s8, 0x18c0000, 0
	s_waitcnt lgkmcnt(0)
	s_add_u32 s6, s6, s8
	s_addc_u32 s7, s7, 0
	s_cmpk_gt_u32 s22, 0x1ef
	s_mov_b64 s[8:9], -1
	s_cbranch_scc0 .LBB0_58
	s_cmpk_gt_u32 s22, 0x237
	s_cbranch_scc0 .LBB0_51
	s_cmpk_gt_u32 s22, 0x277
	s_cbranch_scc0 .LBB0_44
	s_cmpk_gt_u32 s22, 0x377
	s_cbranch_scc0 .LBB0_41
	s_cmpk_gt_u32 s22, 0x8f7
	s_cbranch_scc0 .LBB0_38
	s_cmpk_gt_u32 s22, 0xbb7
	s_cbranch_scc0 .LBB0_35
	s_load_dwordx2 s[8:9], s[0:1], 0x90
	s_add_i32 s14, s22, 0xfffff448
	s_lshl_b64 s[10:11], s[14:15], 12
	v_lshl_add_u64 v[22:23], s[10:11], 0, v[10:11]
	s_and_b64 s[10:11], s[12:13], exec
	s_cselect_b32 s10, 0x40000, 0
	s_waitcnt lgkmcnt(0)
	s_add_u32 s8, s8, s10
	s_addc_u32 s9, s9, 0
	v_lshl_add_u64 v[4:5], v[22:23], 2, s[8:9]
	global_load_dwordx4 v[0:3], v[4:5], off
	s_nop 0
	global_load_dwordx4 v[4:7], v[4:5], off offset:16
	v_lshl_add_u64 v[22:23], v[22:23], 1, s[6:7]
	v_add_co_u32_e32 v22, vcc, 0x18a0000, v22
	s_mov_b64 s[8:9], 0
	s_nop 0
	v_addc_co_u32_e32 v23, vcc, 0, v23, vcc
	s_waitcnt vmcnt(1)
	v_cvt_pk_bf16_f32 v0, v0, v1
	v_cvt_pk_bf16_f32 v1, v2, v3
	s_waitcnt vmcnt(0)
	v_cvt_pk_bf16_f32 v2, v4, v5
	v_cvt_pk_bf16_f32 v3, v6, v7
	global_store_dwordx4 v[22:23], v[0:3], off
.LBB0_35:
	s_andn2_b64 vcc, exec, s[8:9]
	s_cbranch_vccnz .LBB0_37
	s_mov_b64 s[8:9], s[80:81]
	s_and_b64 s[10:11], s[12:13], exec
	s_cselect_b32 s10, 0xb00000, 0
	v_mov_b32_e32 v32, v190
	s_waitcnt lgkmcnt(0)
	s_add_u32 s8, s8, s10
	s_addc_u32 s9, s9, 0
	s_add_i32 s10, s22, 0xf708
	s_and_b32 s11, s10, 0xffff
	s_mul_i32 s11, s11, 0xba2f
	s_lshr_b32 s11, s11, 21
	s_mul_i32 s14, s11, 44
	s_sub_i32 s10, s10, s14
	s_lshl_b32 s10, s10, 6
	s_and_b32 s10, s10, 0xffc0
	v_ashrrev_i32_e32 v33, 4, v32
	v_lshlrev_b32_e32 v0, 2, v32
	v_add_u32_e32 v4, s10, v33
	s_lshl_b32 s11, s11, 6
	v_and_b32_e32 v34, 60, v0
	v_ashrrev_i32_e32 v5, 31, v4
	v_or_b32_e32 v2, s11, v34
	v_lshlrev_b64 v[0:1], 12, v[4:5]
	v_add_u32_e32 v4, 32, v4
	v_lshl_add_u64 v[0:1], s[8:9], 0, v[0:1]
	v_lshlrev_b32_e32 v18, 2, v2
	v_ashrrev_i32_e32 v5, 31, v4
	v_lshl_add_u64 v[0:1], v[0:1], 0, v[18:19]
	v_lshlrev_b64 v[4:5], 12, v[4:5]
	global_load_dwordx4 v[0:3], v[0:1], off
	v_lshl_add_u64 v[4:5], s[8:9], 0, v[4:5]
	v_lshl_add_u64 v[4:5], v[4:5], 0, v[18:19]
	global_load_dwordx4 v[4:7], v[4:5], off
	v_ashrrev_i32_e32 v18, 3, v32
	v_lshlrev_b32_e32 v32, 3, v32
	v_and_b32_e32 v32, 56, v32
	v_mul_lo_u32 v33, v33, s34
	v_lshlrev_b32_e32 v35, 2, v18
	v_lshlrev_b32_e32 v34, 2, v34
	v_mul_u32_u24_e32 v36, 0x104, v32
	v_add3_u32 v33, 0, v34, v33
	v_add3_u32 v34, 0, v36, v35
	v_add_u32_e32 v35, 0x5000, v33
	v_add_u32_e32 v38, 0x5000, v34
	v_mov_b64_e32 v[22:23], s[6:7]
	v_add_u32_e32 v36, 0x5008, v33
	v_add_u32_e32 v37, 0x7080, v33
	v_add_u32_e32 v33, 0x7088, v33
	v_add_u32_e32 v34, 0x5400, v34
	v_add_u32_e32 v18, s11, v18
	v_mad_i64_i32 v[22:23], s[8:9], v18, s35, v[22:23]
	s_lshl_b32 s14, s10, 1
	v_lshl_add_u64 v[22:23], v[22:23], 0, s[14:15]
	v_lshlrev_b32_e32 v18, 1, v32
	v_lshl_add_u64 v[22:23], v[22:23], 0, v[18:19]
	v_add_co_u32_e32 v22, vcc, 0x1320000, v22
	s_waitcnt vmcnt(1)
	ds_write2_b32 v35, v0, v1 offset1:1
	ds_write2_b32 v36, v2, v3 offset1:1
	s_waitcnt vmcnt(0)
	ds_write2_b32 v37, v4, v5 offset1:1
	ds_write2_b32 v33, v6, v7 offset1:1
	s_waitcnt lgkmcnt(0)
	s_barrier
	ds_read2_b32 v[0:1], v38 offset1:65
	ds_read2_b32 v[2:3], v38 offset0:130 offset1:195
	ds_read2_b32 v[4:5], v34 offset0:4 offset1:69
	ds_read2_b32 v[6:7], v34 offset0:134 offset1:199
	v_addc_co_u32_e32 v23, vcc, 0, v23, vcc
	s_waitcnt lgkmcnt(3)
	v_cvt_pk_bf16_f32 v0, v0, v1
	s_waitcnt lgkmcnt(2)
	v_cvt_pk_bf16_f32 v1, v2, v3
	s_waitcnt lgkmcnt(1)
	v_cvt_pk_bf16_f32 v2, v4, v5
	s_waitcnt lgkmcnt(0)
	v_cvt_pk_bf16_f32 v3, v6, v7
	global_store_dwordx4 v[22:23], v[0:3], off
	s_barrier

.LBB0_38:
	s_andn2_b64 vcc, exec, s[8:9]
	s_cbranch_vccnz .LBB0_40
	s_mov_b64 s[8:9], s[78:79]
	s_add_i32 s14, s22, 0xfffffc88
	s_and_b64 s[10:11], s[12:13], exec
	s_cselect_b32 s10, 0x1600000, 0
	v_mov_b32_e32 v32, v190
	s_waitcnt lgkmcnt(0)
	s_add_u32 s8, s8, s10
	s_addc_u32 s9, s9, 0
	s_lshr_b32 s10, s14, 4
	s_lshl_b32 s11, s14, 6
	v_lshlrev_b32_e32 v0, 2, v32
	s_lshl_b32 s14, s10, 5
	v_and_b32_e32 v34, 60, v0
	s_add_i32 s20, s14, 0xb00
	s_and_b32 s11, s11, 0x3c0
	v_ashrrev_i32_e32 v33, 4, v32
	v_and_or_b32 v0, v0, 28, s20
	v_add_u32_e32 v1, s14, v34
	v_cmp_gt_u32_e32 vcc, 32, v34
	v_add_u32_e32 v22, s11, v33
	v_mov_b64_e32 v[4:5], s[8:9]
	v_cndmask_b32_e32 v18, v0, v1, vcc
	v_mad_i64_i32 v[0:1], s[8:9], v22, s38, v[4:5]
	v_lshlrev_b64 v[6:7], 2, v[18:19]
	v_lshl_add_u64 v[0:1], v[0:1], 0, v[6:7]
	v_add_u32_e32 v18, 32, v22
	global_load_dwordx4 v[0:3], v[0:1], off
	v_mad_i64_i32 v[4:5], s[8:9], v18, s38, v[4:5]
	v_lshl_add_u64 v[4:5], v[4:5], 0, v[6:7]
	global_load_dwordx4 v[4:7], v[4:5], off
	v_ashrrev_i32_e32 v18, 3, v32
	v_lshlrev_b32_e32 v32, 3, v32
	v_and_b32_e32 v32, 56, v32
	v_mul_lo_u32 v33, v33, s34
	v_lshlrev_b32_e32 v35, 2, v18
	v_lshlrev_b32_e32 v34, 2, v34
	v_mul_u32_u24_e32 v36, 0x104, v32
	v_add3_u32 v33, 0, v34, v33
	v_add3_u32 v34, 0, v36, v35
	v_add_u32_e32 v35, 0x5000, v33
	v_add_u32_e32 v38, 0x5000, v34
	v_mov_b64_e32 v[22:23], s[6:7]
	v_add_u32_e32 v36, 0x5008, v33
	v_add_u32_e32 v37, 0x7080, v33
	v_add_u32_e32 v33, 0x7088, v33
	v_add_u32_e32 v34, 0x5400, v34
	v_lshl_add_u32 v18, s10, 6, v18
	v_mad_i64_i32 v[22:23], s[8:9], v18, s39, v[22:23]
	s_lshl_b32 s14, s11, 1
	v_lshl_add_u64 v[22:23], v[22:23], 0, s[14:15]
	v_lshlrev_b32_e32 v18, 1, v32
	v_lshl_add_u64 v[22:23], v[22:23], 0, v[18:19]
	v_add_co_u32_e32 v22, vcc, 0x770000, v22
	s_waitcnt vmcnt(1)
	ds_write2_b32 v35, v0, v1 offset1:1
	ds_write2_b32 v36, v2, v3 offset1:1
	s_waitcnt vmcnt(0)
	ds_write2_b32 v37, v4, v5 offset1:1
	ds_write2_b32 v33, v6, v7 offset1:1
	s_waitcnt lgkmcnt(0)
	s_barrier
	ds_read2_b32 v[0:1], v38 offset1:65
	ds_read2_b32 v[2:3], v38 offset0:130 offset1:195
	ds_read2_b32 v[4:5], v34 offset0:4 offset1:69
	ds_read2_b32 v[6:7], v34 offset0:134 offset1:199
	v_addc_co_u32_e32 v23, vcc, 0, v23, vcc
	s_waitcnt lgkmcnt(3)
	v_cvt_pk_bf16_f32 v0, v0, v1
	s_waitcnt lgkmcnt(2)
	v_cvt_pk_bf16_f32 v1, v2, v3
	s_waitcnt lgkmcnt(1)
	v_cvt_pk_bf16_f32 v2, v4, v5
	s_waitcnt lgkmcnt(0)
	v_cvt_pk_bf16_f32 v3, v6, v7
	global_store_dwordx4 v[22:23], v[0:3], off
	s_barrier

.LBB0_41:
	s_andn2_b64 vcc, exec, s[8:9]
	s_cbranch_vccnz .LBB0_43
	s_mov_b64 s[8:9], s[82:83]
	s_add_i32 s14, s22, 0xfffffd88
	s_and_b64 s[10:11], s[12:13], exec
	s_cselect_b32 s10, 0x400000, 0
	v_mov_b32_e32 v32, v190
	s_waitcnt lgkmcnt(0)
	s_add_u32 s8, s8, s10
	s_addc_u32 s9, s9, 0
	s_lshl_b32 s10, s14, 6
	s_and_b32 s10, s10, 0x3c0
	v_ashrrev_i32_e32 v33, 4, v32
	s_lshl_b32 s11, s14, 2
	v_lshlrev_b32_e32 v0, 2, v32
	v_add_u32_e32 v4, s10, v33
	s_and_b32 s11, s11, 0x7fffffc0
	v_and_b32_e32 v34, 60, v0
	v_ashrrev_i32_e32 v5, 31, v4
	v_or_b32_e32 v18, s11, v34
	v_lshlrev_b64 v[0:1], 12, v[4:5]
	v_add_u32_e32 v4, 32, v4
	v_lshl_add_u64 v[0:1], s[8:9], 0, v[0:1]
	v_lshlrev_b64 v[6:7], 2, v[18:19]
	v_ashrrev_i32_e32 v5, 31, v4
	v_lshl_add_u64 v[0:1], v[0:1], 0, v[6:7]
	v_lshlrev_b64 v[4:5], 12, v[4:5]
	global_load_dwordx4 v[0:3], v[0:1], off
	v_lshl_add_u64 v[4:5], s[8:9], 0, v[4:5]
	v_lshl_add_u64 v[4:5], v[4:5], 0, v[6:7]
	global_load_dwordx4 v[4:7], v[4:5], off
	v_ashrrev_i32_e32 v18, 3, v32
	v_lshlrev_b32_e32 v32, 3, v32
	v_and_b32_e32 v32, 56, v32
	v_mul_lo_u32 v33, v33, s34
	v_lshlrev_b32_e32 v35, 2, v18
	v_lshlrev_b32_e32 v34, 2, v34
	v_mul_u32_u24_e32 v36, 0x104, v32
	v_add3_u32 v33, 0, v34, v33
	v_add3_u32 v34, 0, v36, v35
	v_add_u32_e32 v35, 0x5000, v33
	v_add_u32_e32 v38, 0x5000, v34
	v_mov_b64_e32 v[22:23], s[6:7]
	v_add_u32_e32 v36, 0x5008, v33
	v_add_u32_e32 v37, 0x7080, v33
	v_add_u32_e32 v33, 0x7088, v33
	v_add_u32_e32 v34, 0x5400, v34
	v_add_u32_e32 v18, s11, v18
	s_lshl_b32 s14, s10, 1
	v_mad_i64_i32 v[22:23], s[8:9], v18, s39, v[22:23]
	v_lshlrev_b32_e32 v18, 1, v32
	v_lshl_add_u64 v[22:23], v[22:23], 0, s[14:15]
	v_lshl_add_u64 v[22:23], v[22:23], 0, v[18:19]
	v_add_co_u32_e32 v22, vcc, 0x550000, v22
	s_waitcnt vmcnt(1)
	ds_write2_b32 v35, v0, v1 offset1:1
	ds_write2_b32 v36, v2, v3 offset1:1
	s_waitcnt vmcnt(0)
	ds_write2_b32 v37, v4, v5 offset1:1
	ds_write2_b32 v33, v6, v7 offset1:1
	s_waitcnt lgkmcnt(0)
	s_barrier
	ds_read2_b32 v[0:1], v38 offset1:65
	ds_read2_b32 v[2:3], v38 offset0:130 offset1:195
	ds_read2_b32 v[4:5], v34 offset0:4 offset1:69
	ds_read2_b32 v[6:7], v34 offset0:134 offset1:199
	v_addc_co_u32_e32 v23, vcc, 0, v23, vcc
	s_waitcnt lgkmcnt(3)
	v_cvt_pk_bf16_f32 v0, v0, v1
	s_waitcnt lgkmcnt(2)
	v_cvt_pk_bf16_f32 v1, v2, v3
	s_waitcnt lgkmcnt(1)
	v_cvt_pk_bf16_f32 v2, v4, v5
	s_waitcnt lgkmcnt(0)
	v_cvt_pk_bf16_f32 v3, v6, v7
	global_store_dwordx4 v[22:23], v[0:3], off
	s_barrier

.LBB0_58:
	s_andn2_b64 vcc, exec, s[8:9]
	s_cbranch_vccnz .LBB0_60
	s_mov_b64 s[8:9], s[84:85]
	s_and_b64 s[10:11], s[12:13], exec
	s_cselect_b32 s10, 0x7c0000, 0
	v_mov_b32_e32 v32, v190
	s_waitcnt lgkmcnt(0)
	s_add_u32 s8, s8, s10
	s_addc_u32 s9, s9, 0
	s_lshl_b32 s10, s22, 6
	s_lshl_b32 s11, s22, 2
	v_lshlrev_b32_e32 v0, 2, v32
	s_and_b32 s10, s10, 0x3c0
	s_and_b32 s11, s11, 0x7c0
	v_ashrrev_i32_e32 v33, 4, v32
	v_and_b32_e32 v34, 60, v0
	v_or_b32_e32 v2, s11, v34
	v_add_u32_e32 v6, s10, v33
	v_mov_b64_e32 v[4:5], s[8:9]
	v_mad_i64_i32 v[0:1], s[8:9], v6, s41, v[4:5]
	v_lshlrev_b32_e32 v18, 2, v2
	v_lshl_add_u64 v[0:1], v[0:1], 0, v[18:19]
	v_add_u32_e32 v6, 32, v6
	global_load_dwordx4 v[0:3], v[0:1], off
	v_mad_i64_i32 v[4:5], s[8:9], v6, s41, v[4:5]
	v_lshl_add_u64 v[4:5], v[4:5], 0, v[18:19]
	global_load_dwordx4 v[4:7], v[4:5], off
	v_ashrrev_i32_e32 v18, 3, v32
	v_lshlrev_b32_e32 v32, 3, v32
	v_and_b32_e32 v32, 56, v32
	v_mul_lo_u32 v33, v33, s34
	v_lshlrev_b32_e32 v35, 2, v18
	v_lshlrev_b32_e32 v34, 2, v34
	v_mul_u32_u24_e32 v36, 0x104, v32
	v_add3_u32 v33, 0, v34, v33
	v_add3_u32 v34, 0, v36, v35
	v_add_u32_e32 v35, 0x5000, v33
	v_add_u32_e32 v38, 0x5000, v34
	v_add_u32_e32 v36, 0x5008, v33
	v_add_u32_e32 v37, 0x7080, v33
	v_add_u32_e32 v33, 0x7088, v33
	v_add_u32_e32 v34, 0x5400, v34
	v_mov_b64_e32 v[22:23], s[6:7]
	v_add_u32_e32 v18, s11, v18
	s_lshl_b32 s14, s10, 1
	v_mad_i64_i32 v[22:23], s[6:7], v18, s39, v[22:23]
	v_lshl_add_u64 v[22:23], v[22:23], 0, s[14:15]
	v_lshlrev_b32_e32 v18, 1, v32
	v_lshl_add_u64 v[22:23], v[22:23], 0, v[18:19]
	s_waitcnt vmcnt(1)
	ds_write2_b32 v35, v0, v1 offset1:1
	ds_write2_b32 v36, v2, v3 offset1:1
	s_waitcnt vmcnt(0)
	ds_write2_b32 v37, v4, v5 offset1:1
	ds_write2_b32 v33, v6, v7 offset1:1
	s_waitcnt lgkmcnt(0)
	s_barrier
	ds_read2_b32 v[0:1], v38 offset1:65
	ds_read2_b32 v[2:3], v38 offset0:130 offset1:195
	ds_read2_b32 v[4:5], v34 offset0:4 offset1:69
	ds_read2_b32 v[6:7], v34 offset0:134 offset1:199
	s_waitcnt lgkmcnt(3)
	v_cvt_pk_bf16_f32 v0, v0, v1
	s_waitcnt lgkmcnt(2)
	v_cvt_pk_bf16_f32 v1, v2, v3
	s_waitcnt lgkmcnt(1)
	v_cvt_pk_bf16_f32 v2, v4, v5
	s_waitcnt lgkmcnt(0)
	v_cvt_pk_bf16_f32 v3, v6, v7
	global_store_dwordx4 v[22:23], v[0:3], off
	s_barrier
